# A/B item conv: first and last passes peeled, packed FMAs against structurally zero taps (pad rows 31-35, negative taps) removed
# speedup vs baseline: 1.5550x; 1.0013x over previous
.LBB0_833:
	s_or_b64 exec, exec, s[2:3]
	v_lshlrev_b32_e32 v122, 2, v86
	v_mov_b64_e32 v[86:87], v[190:191]
	v_mov_b64_e32 v[88:89], v[192:193]
	v_mov_b64_e32 v[82:83], v[186:187]
	v_mov_b64_e32 v[84:85], v[188:189]
	s_movk_i32 s2, 0xc00
	v_mul_lo_u32 v123, v152, s2
	v_or_b32_e32 v90, v123, v154
	s_add_i32 s2, 32, 0xd800
	v_add_u32_e32 v170, s2, v90
	v_add_u32_e32 v151, 32, v154
	s_mov_b32 s2, -4
	v_mov_b64_e32 v[144:145], v[86:87]
	v_mov_b64_e32 v[140:141], v[82:83]
	v_mov_b64_e32 v[142:143], v[84:85]
	v_mov_b64_e32 v[146:147], v[88:89]
	v_mov_b64_e32 v[132:133], v[82:83]
	v_mov_b64_e32 v[134:135], v[84:85]
	v_mov_b64_e32 v[136:137], v[86:87]
	v_mov_b64_e32 v[138:139], v[88:89]
	v_mov_b64_e32 v[124:125], v[82:83]
	v_mov_b64_e32 v[126:127], v[84:85]
	v_mov_b64_e32 v[128:129], v[86:87]
	v_mov_b64_e32 v[130:131], v[88:89]
	ds_read_b128 v[114:117], v170
	s_add_i32 s2, s2, 4
	s_cmp_gt_u32 s2, 31
	s_waitcnt lgkmcnt(0)
	v_lshlrev_b32_e32 v172, 16, v114
	v_and_b32_e32 v173, 0xffff0000, v114
	v_lshlrev_b32_e32 v174, 16, v115
	v_and_b32_e32 v175, 0xffff0000, v115
	v_lshlrev_b32_e32 v176, 16, v116
	v_and_b32_e32 v177, 0xffff0000, v116
	v_lshlrev_b32_e32 v178, 16, v117
	v_and_b32_e32 v179, 0xffff0000, v117
	ds_read_b128 v[114:117], v151
	ds_read_b128 v[118:121], v151 offset:768
	s_waitcnt lgkmcnt(1)
	v_pk_fma_f32 v[182:183], v[114:115], v[172:173], v[82:83]
	v_pk_fma_f32 v[184:185], v[116:117], v[174:175], v[84:85]
	ds_read_b128 v[82:85], v170 offset:768
	ds_read_b128 v[90:93], v151 offset:1536
	ds_read_b128 v[94:97], v151 offset:2304
	s_waitcnt lgkmcnt(3)
	v_pk_fma_f32 v[88:89], v[120:121], v[178:179], v[88:89]
	s_waitcnt lgkmcnt(2)
	v_lshlrev_b32_e32 v172, 16, v82
	v_and_b32_e32 v173, 0xffff0000, v82
	v_lshlrev_b32_e32 v82, 16, v83
	v_and_b32_e32 v83, 0xffff0000, v83
	v_lshlrev_b32_e32 v174, 16, v84
	v_and_b32_e32 v175, 0xffff0000, v84
	v_lshlrev_b32_e32 v84, 16, v85
	v_and_b32_e32 v85, 0xffff0000, v85
	s_waitcnt lgkmcnt(1)
	v_pk_fma_f32 v[178:179], v[92:93], v[82:83], v[184:185]
	s_waitcnt lgkmcnt(0)
	v_pk_fma_f32 v[88:89], v[96:97], v[84:85], v[88:89]
	v_pk_fma_f32 v[142:143], v[116:117], v[82:83], v[142:143]
	v_pk_fma_f32 v[146:147], v[120:121], v[84:85], v[146:147]
	ds_read_b128 v[82:85], v170 offset:1536
	ds_read_b128 v[98:101], v151 offset:3072
	ds_read_b128 v[102:105], v151 offset:3840
	v_pk_fma_f32 v[86:87], v[118:119], v[176:177], v[86:87]
	v_pk_fma_f32 v[176:177], v[90:91], v[172:173], v[182:183]
	v_pk_fma_f32 v[86:87], v[94:95], v[174:175], v[86:87]
	v_pk_fma_f32 v[140:141], v[114:115], v[172:173], v[140:141]
	v_pk_fma_f32 v[144:145], v[118:119], v[174:175], v[144:145]
	s_waitcnt lgkmcnt(2)
	v_lshlrev_b32_e32 v172, 16, v82
	v_and_b32_e32 v173, 0xffff0000, v82
	v_lshlrev_b32_e32 v82, 16, v83
	v_and_b32_e32 v83, 0xffff0000, v83
	v_lshlrev_b32_e32 v174, 16, v84
	v_and_b32_e32 v175, 0xffff0000, v84
	v_lshlrev_b32_e32 v84, 16, v85
	v_and_b32_e32 v85, 0xffff0000, v85
	s_waitcnt lgkmcnt(1)
	v_pk_fma_f32 v[178:179], v[100:101], v[82:83], v[178:179]
	s_waitcnt lgkmcnt(0)
	v_pk_fma_f32 v[88:89], v[104:105], v[84:85], v[88:89]
	v_pk_fma_f32 v[142:143], v[92:93], v[82:83], v[142:143]
	v_pk_fma_f32 v[146:147], v[96:97], v[84:85], v[146:147]
	v_pk_fma_f32 v[134:135], v[116:117], v[82:83], v[134:135]
	v_pk_fma_f32 v[138:139], v[120:121], v[84:85], v[138:139]
	ds_read_b128 v[82:85], v170 offset:2304
	ds_read_b128 v[106:109], v151 offset:4608
	ds_read_b128 v[110:113], v151 offset:5376
	v_pk_fma_f32 v[176:177], v[98:99], v[172:173], v[176:177]
	v_pk_fma_f32 v[86:87], v[102:103], v[174:175], v[86:87]
	v_pk_fma_f32 v[140:141], v[90:91], v[172:173], v[140:141]
	v_pk_fma_f32 v[144:145], v[94:95], v[174:175], v[144:145]
	v_pk_fma_f32 v[132:133], v[114:115], v[172:173], v[132:133]
	v_pk_fma_f32 v[136:137], v[118:119], v[174:175], v[136:137]
	s_waitcnt lgkmcnt(2)
	v_lshlrev_b32_e32 v172, 16, v82
	v_and_b32_e32 v173, 0xffff0000, v82
	v_lshlrev_b32_e32 v174, 16, v83
	v_and_b32_e32 v175, 0xffff0000, v83
	v_lshlrev_b32_e32 v182, 16, v84
	v_and_b32_e32 v183, 0xffff0000, v84
	v_lshlrev_b32_e32 v184, 16, v85
	v_and_b32_e32 v185, 0xffff0000, v85
	s_waitcnt lgkmcnt(1)
	v_pk_fma_f32 v[82:83], v[106:107], v[172:173], v[176:177]
	v_pk_fma_f32 v[84:85], v[108:109], v[174:175], v[178:179]
	s_waitcnt lgkmcnt(0)
	v_pk_fma_f32 v[86:87], v[110:111], v[182:183], v[86:87]
	v_pk_fma_f32 v[88:89], v[112:113], v[184:185], v[88:89]
	v_pk_fma_f32 v[140:141], v[98:99], v[172:173], v[140:141]
	v_pk_fma_f32 v[142:143], v[100:101], v[174:175], v[142:143]
	v_pk_fma_f32 v[144:145], v[102:103], v[182:183], v[144:145]
	v_pk_fma_f32 v[146:147], v[104:105], v[184:185], v[146:147]
	v_pk_fma_f32 v[132:133], v[90:91], v[172:173], v[132:133]
	v_pk_fma_f32 v[134:135], v[92:93], v[174:175], v[134:135]
	v_pk_fma_f32 v[136:137], v[94:95], v[182:183], v[136:137]
	v_pk_fma_f32 v[138:139], v[96:97], v[184:185], v[138:139]
	v_pk_fma_f32 v[124:125], v[114:115], v[172:173], v[124:125]
	v_pk_fma_f32 v[126:127], v[116:117], v[174:175], v[126:127]
	v_pk_fma_f32 v[128:129], v[118:119], v[182:183], v[128:129]
	v_pk_fma_f32 v[130:131], v[120:121], v[184:185], v[130:131]
	v_add_u32_e32 v151, 0x1800, v151
	v_add_u32_e32 v170, 0xc00, v170
.LBB0_834:
	ds_read_b128 v[114:117], v170
	s_add_i32 s2, s2, 4
	s_cmp_gt_u32 s2, 27
	s_waitcnt lgkmcnt(0)
	v_lshlrev_b32_e32 v172, 16, v114
	v_and_b32_e32 v173, 0xffff0000, v114
	v_lshlrev_b32_e32 v174, 16, v115
	v_and_b32_e32 v175, 0xffff0000, v115
	v_lshlrev_b32_e32 v176, 16, v116
	v_and_b32_e32 v177, 0xffff0000, v116
	v_lshlrev_b32_e32 v178, 16, v117
	v_and_b32_e32 v179, 0xffff0000, v117
	ds_read_b128 v[114:117], v151
	ds_read_b128 v[118:121], v151 offset:768
	v_pk_fma_f32 v[124:125], v[90:91], v[172:173], v[124:125]
	v_pk_fma_f32 v[126:127], v[92:93], v[174:175], v[126:127]
	v_pk_fma_f32 v[128:129], v[94:95], v[176:177], v[128:129]
	s_waitcnt lgkmcnt(1)
	v_pk_fma_f32 v[182:183], v[114:115], v[172:173], v[82:83]
	v_pk_fma_f32 v[184:185], v[116:117], v[174:175], v[84:85]
	ds_read_b128 v[82:85], v170 offset:768
	v_pk_fma_f32 v[130:131], v[96:97], v[178:179], v[130:131]
	ds_read_b128 v[90:93], v151 offset:1536
	ds_read_b128 v[94:97], v151 offset:2304
	s_waitcnt lgkmcnt(3)
	v_pk_fma_f32 v[88:89], v[120:121], v[178:179], v[88:89]
	v_pk_fma_f32 v[140:141], v[106:107], v[172:173], v[140:141]
	v_pk_fma_f32 v[142:143], v[108:109], v[174:175], v[142:143]
	v_pk_fma_f32 v[146:147], v[112:113], v[178:179], v[146:147]
	v_pk_fma_f32 v[132:133], v[98:99], v[172:173], v[132:133]
	v_pk_fma_f32 v[134:135], v[100:101], v[174:175], v[134:135]
	v_pk_fma_f32 v[138:139], v[104:105], v[178:179], v[138:139]
	s_waitcnt lgkmcnt(2)
	v_lshlrev_b32_e32 v172, 16, v82
	v_and_b32_e32 v173, 0xffff0000, v82
	v_lshlrev_b32_e32 v82, 16, v83
	v_and_b32_e32 v83, 0xffff0000, v83
	v_lshlrev_b32_e32 v174, 16, v84
	v_and_b32_e32 v175, 0xffff0000, v84
	v_lshlrev_b32_e32 v84, 16, v85
	v_and_b32_e32 v85, 0xffff0000, v85
	s_waitcnt lgkmcnt(1)
	v_pk_fma_f32 v[178:179], v[92:93], v[82:83], v[184:185]
	s_waitcnt lgkmcnt(0)
	v_pk_fma_f32 v[88:89], v[96:97], v[84:85], v[88:89]
	v_pk_fma_f32 v[142:143], v[116:117], v[82:83], v[142:143]
	v_pk_fma_f32 v[146:147], v[120:121], v[84:85], v[146:147]
	v_pk_fma_f32 v[134:135], v[108:109], v[82:83], v[134:135]
	v_pk_fma_f32 v[138:139], v[112:113], v[84:85], v[138:139]
	v_pk_fma_f32 v[126:127], v[100:101], v[82:83], v[126:127]
	v_pk_fma_f32 v[130:131], v[104:105], v[84:85], v[130:131]
	ds_read_b128 v[82:85], v170 offset:1536
	v_pk_fma_f32 v[136:137], v[102:103], v[176:177], v[136:137]
	v_pk_fma_f32 v[124:125], v[98:99], v[172:173], v[124:125]
	v_pk_fma_f32 v[128:129], v[102:103], v[174:175], v[128:129]
	ds_read_b128 v[98:101], v151 offset:3072
	ds_read_b128 v[102:105], v151 offset:3840
	v_pk_fma_f32 v[86:87], v[118:119], v[176:177], v[86:87]
	v_pk_fma_f32 v[144:145], v[110:111], v[176:177], v[144:145]
	v_pk_fma_f32 v[176:177], v[90:91], v[172:173], v[182:183]
	v_pk_fma_f32 v[86:87], v[94:95], v[174:175], v[86:87]
	v_pk_fma_f32 v[140:141], v[114:115], v[172:173], v[140:141]
	v_pk_fma_f32 v[144:145], v[118:119], v[174:175], v[144:145]
	v_pk_fma_f32 v[132:133], v[106:107], v[172:173], v[132:133]
	v_pk_fma_f32 v[136:137], v[110:111], v[174:175], v[136:137]
	s_waitcnt lgkmcnt(2)
	v_lshlrev_b32_e32 v172, 16, v82
	v_and_b32_e32 v173, 0xffff0000, v82
	v_lshlrev_b32_e32 v82, 16, v83
	v_and_b32_e32 v83, 0xffff0000, v83
	v_lshlrev_b32_e32 v174, 16, v84
	v_and_b32_e32 v175, 0xffff0000, v84
	v_lshlrev_b32_e32 v84, 16, v85
	v_and_b32_e32 v85, 0xffff0000, v85
	s_waitcnt lgkmcnt(1)
	v_pk_fma_f32 v[178:179], v[100:101], v[82:83], v[178:179]
	s_waitcnt lgkmcnt(0)
	v_pk_fma_f32 v[88:89], v[104:105], v[84:85], v[88:89]
	v_pk_fma_f32 v[142:143], v[92:93], v[82:83], v[142:143]
	v_pk_fma_f32 v[146:147], v[96:97], v[84:85], v[146:147]
	v_pk_fma_f32 v[134:135], v[116:117], v[82:83], v[134:135]
	v_pk_fma_f32 v[138:139], v[120:121], v[84:85], v[138:139]
	v_pk_fma_f32 v[126:127], v[108:109], v[82:83], v[126:127]
	v_pk_fma_f32 v[130:131], v[112:113], v[84:85], v[130:131]
	ds_read_b128 v[82:85], v170 offset:2304
	v_pk_fma_f32 v[124:125], v[106:107], v[172:173], v[124:125]
	v_pk_fma_f32 v[128:129], v[110:111], v[174:175], v[128:129]
	ds_read_b128 v[106:109], v151 offset:4608
	ds_read_b128 v[110:113], v151 offset:5376
	v_pk_fma_f32 v[176:177], v[98:99], v[172:173], v[176:177]
	v_pk_fma_f32 v[86:87], v[102:103], v[174:175], v[86:87]
	v_pk_fma_f32 v[140:141], v[90:91], v[172:173], v[140:141]
	v_pk_fma_f32 v[144:145], v[94:95], v[174:175], v[144:145]
	v_pk_fma_f32 v[132:133], v[114:115], v[172:173], v[132:133]
	v_pk_fma_f32 v[136:137], v[118:119], v[174:175], v[136:137]
	s_waitcnt lgkmcnt(2)
	v_lshlrev_b32_e32 v172, 16, v82
	v_and_b32_e32 v173, 0xffff0000, v82
	v_lshlrev_b32_e32 v174, 16, v83
	v_and_b32_e32 v175, 0xffff0000, v83
	v_lshlrev_b32_e32 v182, 16, v84
	v_and_b32_e32 v183, 0xffff0000, v84
	v_lshlrev_b32_e32 v184, 16, v85
	v_and_b32_e32 v185, 0xffff0000, v85
	s_waitcnt lgkmcnt(1)
	v_pk_fma_f32 v[82:83], v[106:107], v[172:173], v[176:177]
	v_pk_fma_f32 v[84:85], v[108:109], v[174:175], v[178:179]
	s_waitcnt lgkmcnt(0)
	v_pk_fma_f32 v[86:87], v[110:111], v[182:183], v[86:87]
	v_pk_fma_f32 v[88:89], v[112:113], v[184:185], v[88:89]
	v_pk_fma_f32 v[140:141], v[98:99], v[172:173], v[140:141]
	v_pk_fma_f32 v[142:143], v[100:101], v[174:175], v[142:143]
	v_pk_fma_f32 v[144:145], v[102:103], v[182:183], v[144:145]
	v_pk_fma_f32 v[146:147], v[104:105], v[184:185], v[146:147]
	v_pk_fma_f32 v[132:133], v[90:91], v[172:173], v[132:133]
	v_pk_fma_f32 v[134:135], v[92:93], v[174:175], v[134:135]
	v_pk_fma_f32 v[136:137], v[94:95], v[182:183], v[136:137]
	v_pk_fma_f32 v[138:139], v[96:97], v[184:185], v[138:139]
	v_pk_fma_f32 v[124:125], v[114:115], v[172:173], v[124:125]
	v_pk_fma_f32 v[126:127], v[116:117], v[174:175], v[126:127]
	v_pk_fma_f32 v[128:129], v[118:119], v[182:183], v[128:129]
	v_pk_fma_f32 v[130:131], v[120:121], v[184:185], v[130:131]
	v_add_u32_e32 v151, 0x1800, v151
	v_add_u32_e32 v170, 0xc00, v170
	s_cbranch_scc0 .LBB0_834
	ds_read_b128 v[114:117], v170
	ds_read_b128 v[118:121], v170 offset:768
	s_waitcnt lgkmcnt(1)
	v_lshlrev_b32_e32 v172, 16, v114
	v_and_b32_e32 v173, 0xffff0000, v114
	v_lshlrev_b32_e32 v174, 16, v115
	v_and_b32_e32 v175, 0xffff0000, v115
	v_lshlrev_b32_e32 v176, 16, v116
	v_and_b32_e32 v177, 0xffff0000, v116
	v_lshlrev_b32_e32 v178, 16, v117
	v_and_b32_e32 v179, 0xffff0000, v117
	v_pk_fma_f32 v[132:133], v[98:99], v[172:173], v[132:133]
	v_pk_fma_f32 v[134:135], v[100:101], v[174:175], v[134:135]
	v_pk_fma_f32 v[136:137], v[102:103], v[176:177], v[136:137]
	v_pk_fma_f32 v[138:139], v[104:105], v[178:179], v[138:139]
	v_pk_fma_f32 v[124:125], v[90:91], v[172:173], v[124:125]
	v_pk_fma_f32 v[126:127], v[92:93], v[174:175], v[126:127]
	v_pk_fma_f32 v[128:129], v[94:95], v[176:177], v[128:129]
	v_pk_fma_f32 v[130:131], v[96:97], v[178:179], v[130:131]
	s_waitcnt lgkmcnt(0)
	v_lshlrev_b32_e32 v172, 16, v118
	v_and_b32_e32 v173, 0xffff0000, v118
	v_lshlrev_b32_e32 v174, 16, v119
	v_and_b32_e32 v175, 0xffff0000, v119
	v_lshlrev_b32_e32 v176, 16, v120
	v_and_b32_e32 v177, 0xffff0000, v120
	v_lshlrev_b32_e32 v178, 16, v121
	v_and_b32_e32 v179, 0xffff0000, v121
	v_pk_fma_f32 v[124:125], v[98:99], v[172:173], v[124:125]
	v_pk_fma_f32 v[126:127], v[100:101], v[174:175], v[126:127]
	v_pk_fma_f32 v[128:129], v[102:103], v[176:177], v[128:129]
	v_pk_fma_f32 v[130:131], v[104:105], v[178:179], v[130:131]
	s_waitcnt vmcnt(0)
	v_mov_b32_e32 v149, v66
	v_mov_b32_e32 v153, v67
	v_mov_b32_e32 v164, v68
	v_mov_b32_e32 v165, v69
	v_mov_b32_e32 v166, v62
	v_mov_b32_e32 v167, v63
	v_mov_b32_e32 v168, v64
	v_mov_b32_e32 v169, v65
	s_ashr_i32 s6, s6, 6
	s_cmpk_eq_i32 s7, 0x7e0
	s_cselect_b64 s[36:37], -1, 0
	s_and_b64 s[2:3], s[36:37], s[38:39]
	s_and_saveexec_b64 s[10:11], s[2:3]
	s_cbranch_execz .LBB0_840
	v_add_u32_e32 v90, 32, v123
	s_mov_b32 s2, 0xd800
	v_add3_u32 v90, v90, v154, s2
	s_add_i32 s2, s6, s4
	s_mul_i32 s12, s2, 30
	s_ashr_i32 s13, s12, 31
	v_cmp_lt_i32_e32 vcc, 0, v152
	s_and_saveexec_b64 s[2:3], vcc
	s_cbranch_execz .LBB0_838
	v_readlane_b32 s16, v243, 31
	v_add_u32_e32 v92, -2, v150
	v_mov_b32_e32 v93, v155
	v_readlane_b32 s17, v243, 32
	v_lshl_add_u64 v[92:93], v[92:93], 0, s[12:13]
	s_movk_i32 s7, 0x600
	v_mov_b64_e32 v[104:105], s[16:17]
	v_mad_u64_u32 v[94:95], s[16:17], v92, s7, v[104:105]
	v_mad_i32_i24 v95, v93, s7, v95
	v_mov_b32_e32 v123, v155
	v_lshl_add_u64 v[106:107], v[94:95], 0, v[122:123]
	ds_read_b128 v[92:95], v90 offset:23040
	s_waitcnt lgkmcnt(0)
	v_lshlrev_b32_e32 v98, 16, v93
	v_lshlrev_b32_e32 v96, 16, v92
	v_and_b32_e32 v99, 0xffff0000, v93
	v_and_b32_e32 v97, 0xffff0000, v92
	v_add_u32_e32 v92, -1, v150
	v_mov_b32_e32 v93, v155
	v_lshl_add_u64 v[92:93], v[92:93], 0, s[12:13]
	v_lshlrev_b32_e32 v102, 16, v95
	v_lshlrev_b32_e32 v100, 16, v94
	v_and_b32_e32 v103, 0xffff0000, v95
	v_and_b32_e32 v101, 0xffff0000, v94
	v_mad_u64_u32 v[94:95], s[16:17], v92, s7, v[104:105]
	global_store_dwordx4 v[106:107], v[100:103], off offset:16
	global_store_dwordx4 v[106:107], v[96:99], off
	v_mad_i32_i24 v95, v93, s7, v95
	v_lshl_add_u64 v[104:105], v[94:95], 0, v[122:123]
	ds_read_b128 v[92:95], v90 offset:23808
	s_waitcnt lgkmcnt(0)
	v_lshlrev_b32_e32 v102, 16, v95
	v_lshlrev_b32_e32 v100, 16, v94
	v_and_b32_e32 v103, 0xffff0000, v95
	v_and_b32_e32 v101, 0xffff0000, v94
	v_lshlrev_b32_e32 v98, 16, v93
	v_lshlrev_b32_e32 v96, 16, v92
	v_and_b32_e32 v99, 0xffff0000, v93
	v_and_b32_e32 v97, 0xffff0000, v92
	global_store_dwordx4 v[104:105], v[100:103], off offset:16
	global_store_dwordx4 v[104:105], v[96:99], off
